# HGRN2 chunk scan decay pass regenerated: q re-reads issued first, bf16 rounding of q and k via v_cvt_pk_bf16_f32 pairs (k pair = packed k^T dword) instead of integer bit tricks + perm
# speedup vs baseline: 1.0054x; 1.0054x over previous
.LBB0_466:
	s_or_b64 exec, exec, s[4:5]
	s_waitcnt lgkmcnt(0)
	ds_read_u16 v224, v43
	ds_read_u16 v225, v45
	ds_read_u16 v226, v76
	ds_read_u16 v227, v77
	ds_read_u16 v228, v78
	ds_read_u16 v229, v79
	ds_read_u16 v230, v80
	ds_read_u16 v231, v81
	ds_read_u16 v232, v82
	ds_read_u16 v233, v43 offset:2448
	ds_read_u16 v234, v43 offset:2720
	ds_read_u16 v235, v43 offset:2992
	ds_read_u16 v236, v43 offset:3264
	ds_read_u16 v237, v43 offset:3536
	ds_read_u16 v238, v43 offset:3808
	ds_read_u16 v239, v43 offset:4080
	v_mul_f32_e32 v242, v64, v102
	v_mul_f32_e32 v116, v116, v102
	v_rcp_f32_e32 v240, v242
	v_rcp_f32_e32 v241, v116
	v_pk_add_f32 v[64:65], v[64:65], 1.0 op_sel_hi:[1,0] neg_lo:[1,0] neg_hi:[1,0]
	s_nop 0
	v_pk_mul_f32 v[64:65], v[64:65], v[240:241]
	s_waitcnt lgkmcnt(14)
	v_lshlrev_b32_e32 v224, 16, v224
	v_lshlrev_b32_e32 v225, 16, v225
	v_mul_f32_e32 v224, v242, v224
	v_mul_f32_e32 v225, v116, v225
	v_cvt_pk_bf16_f32 v224, v224, v225
	v_cvt_pk_bf16_f32 v244, v64, v65
	ds_write_b16 v43, v224
	ds_write_b16_d16_hi v45, v224
	ds_write_b16 v43, v244 offset:17408
	ds_write_b16_d16_hi v45, v244 offset:17408
	v_mul_f32_e32 v115, v115, v102
	v_mul_f32_e32 v114, v114, v102
	v_rcp_f32_e32 v240, v115
	v_rcp_f32_e32 v241, v114
	v_pk_add_f32 v[62:63], v[62:63], 1.0 op_sel_hi:[1,0] neg_lo:[1,0] neg_hi:[1,0]
	s_nop 0
	v_pk_mul_f32 v[62:63], v[62:63], v[240:241]
	s_waitcnt lgkmcnt(14)
	v_lshlrev_b32_e32 v226, 16, v226
	v_lshlrev_b32_e32 v227, 16, v227
	v_mul_f32_e32 v226, v115, v226
	v_mul_f32_e32 v227, v114, v227
	v_cvt_pk_bf16_f32 v226, v226, v227
	v_cvt_pk_bf16_f32 v245, v62, v63
	ds_write_b16 v76, v226
	ds_write_b16_d16_hi v77, v226
	ds_write_b16 v76, v245 offset:17408
	ds_write_b16_d16_hi v77, v245 offset:17408
	v_mul_f32_e32 v113, v113, v102
	v_mul_f32_e32 v112, v112, v102
	v_rcp_f32_e32 v240, v113
	v_rcp_f32_e32 v241, v112
	v_pk_add_f32 v[60:61], v[60:61], 1.0 op_sel_hi:[1,0] neg_lo:[1,0] neg_hi:[1,0]
	s_nop 0
	v_pk_mul_f32 v[60:61], v[60:61], v[240:241]
	s_waitcnt lgkmcnt(14)
	v_lshlrev_b32_e32 v228, 16, v228
	v_lshlrev_b32_e32 v229, 16, v229
	v_mul_f32_e32 v228, v113, v228
	v_mul_f32_e32 v229, v112, v229
	v_cvt_pk_bf16_f32 v228, v228, v229
	v_cvt_pk_bf16_f32 v246, v60, v61
	ds_write_b16 v78, v228
	ds_write_b16_d16_hi v79, v228
	ds_write_b16 v78, v246 offset:17408
	ds_write_b16_d16_hi v79, v246 offset:17408
	v_mul_f32_e32 v111, v111, v102
	v_mul_f32_e32 v110, v110, v102
	v_rcp_f32_e32 v240, v111
	v_rcp_f32_e32 v241, v110
	v_pk_add_f32 v[58:59], v[58:59], 1.0 op_sel_hi:[1,0] neg_lo:[1,0] neg_hi:[1,0]
	s_nop 0
	v_pk_mul_f32 v[58:59], v[58:59], v[240:241]
	s_waitcnt lgkmcnt(14)
	v_lshlrev_b32_e32 v230, 16, v230
	v_lshlrev_b32_e32 v231, 16, v231
	v_mul_f32_e32 v230, v111, v230
	v_mul_f32_e32 v231, v110, v231
	v_cvt_pk_bf16_f32 v230, v230, v231
	v_cvt_pk_bf16_f32 v247, v58, v59
	ds_write_b16 v80, v230
	ds_write_b16_d16_hi v81, v230
	ds_write_b16 v80, v247 offset:17408
	ds_write_b16_d16_hi v81, v247 offset:17408
	ds_write_b128 v94, v[244:247] offset:34816
	v_mul_f32_e32 v109, v109, v102
	v_mul_f32_e32 v108, v108, v102
	v_rcp_f32_e32 v240, v109
	v_rcp_f32_e32 v241, v108
	v_pk_add_f32 v[56:57], v[56:57], 1.0 op_sel_hi:[1,0] neg_lo:[1,0] neg_hi:[1,0]
	s_nop 0
	v_pk_mul_f32 v[56:57], v[56:57], v[240:241]
	s_waitcnt lgkmcnt(14)
	v_lshlrev_b32_e32 v232, 16, v232
	v_lshlrev_b32_e32 v233, 16, v233
	v_mul_f32_e32 v232, v109, v232
	v_mul_f32_e32 v233, v108, v233
	v_cvt_pk_bf16_f32 v232, v232, v233
	v_cvt_pk_bf16_f32 v244, v56, v57
	ds_write_b16 v82, v232
	ds_write_b16_d16_hi v43, v232 offset:2448
	ds_write_b16 v82, v244 offset:17408
	ds_write_b16_d16_hi v43, v244 offset:19856
	v_mul_f32_e32 v107, v107, v102
	v_mul_f32_e32 v106, v106, v102
	v_rcp_f32_e32 v240, v107
	v_rcp_f32_e32 v241, v106
	v_pk_add_f32 v[54:55], v[54:55], 1.0 op_sel_hi:[1,0] neg_lo:[1,0] neg_hi:[1,0]
	s_nop 0
	v_pk_mul_f32 v[54:55], v[54:55], v[240:241]
	s_waitcnt lgkmcnt(14)
	v_lshlrev_b32_e32 v234, 16, v234
	v_lshlrev_b32_e32 v235, 16, v235
	v_mul_f32_e32 v234, v107, v234
	v_mul_f32_e32 v235, v106, v235
	v_cvt_pk_bf16_f32 v234, v234, v235
	v_cvt_pk_bf16_f32 v245, v54, v55
	ds_write_b16 v43, v234 offset:2720
	ds_write_b16_d16_hi v43, v234 offset:2992
	ds_write_b16 v43, v245 offset:20128
	ds_write_b16_d16_hi v43, v245 offset:20400
	v_mul_f32_e32 v105, v105, v102
	v_mul_f32_e32 v104, v104, v102
	v_rcp_f32_e32 v240, v105
	v_rcp_f32_e32 v241, v104
	v_pk_add_f32 v[52:53], v[52:53], 1.0 op_sel_hi:[1,0] neg_lo:[1,0] neg_hi:[1,0]
	s_nop 0
	v_pk_mul_f32 v[52:53], v[52:53], v[240:241]
	s_waitcnt lgkmcnt(14)
	v_lshlrev_b32_e32 v236, 16, v236
	v_lshlrev_b32_e32 v237, 16, v237
	v_mul_f32_e32 v236, v105, v236
	v_mul_f32_e32 v237, v104, v237
	v_cvt_pk_bf16_f32 v236, v236, v237
	v_cvt_pk_bf16_f32 v246, v52, v53
	ds_write_b16 v43, v236 offset:3264
	ds_write_b16_d16_hi v43, v236 offset:3536
	ds_write_b16 v43, v246 offset:20672
	ds_write_b16_d16_hi v43, v246 offset:20944
	v_mul_f32_e32 v103, v103, v102
	v_mul_f32_e32 v101, v101, v102
	v_rcp_f32_e32 v240, v103
	v_rcp_f32_e32 v241, v101
	v_pk_add_f32 v[50:51], v[50:51], 1.0 op_sel_hi:[1,0] neg_lo:[1,0] neg_hi:[1,0]
	s_nop 0
	v_pk_mul_f32 v[50:51], v[50:51], v[240:241]
	s_waitcnt lgkmcnt(14)
	v_lshlrev_b32_e32 v238, 16, v238
	v_lshlrev_b32_e32 v239, 16, v239
	v_mul_f32_e32 v238, v103, v238
	v_mul_f32_e32 v239, v101, v239
	v_cvt_pk_bf16_f32 v238, v238, v239
	v_cvt_pk_bf16_f32 v247, v50, v51
	ds_write_b16 v43, v238 offset:3808
	ds_write_b16_d16_hi v43, v238 offset:4080
	ds_write_b16 v43, v247 offset:21216
	ds_write_b16_d16_hi v43, v247 offset:21488
	ds_write_b128 v94, v[244:247] offset:34832
	s_waitcnt lgkmcnt(0)
	s_barrier
	s_and_saveexec_b64 s[6:7], s[42:43]
	s_cbranch_execz .LBB0_468
	ds_read_b128 v[50:53], v95
	ds_read_b128 v[54:57], v95 offset:64
	ds_read_b128 v[58:61], v95 offset:128
	ds_read_b128 v[62:65], v95 offset:192
	ds_read_b128 v[66:69], v99 offset:17408
	ds_read_b128 v[102:105], v99 offset:17472
	ds_read_b128 v[106:109], v99 offset:17536
	ds_read_b128 v[110:113], v99 offset:17600
	ds_read_b128 v[114:117], v99 offset:21760
	ds_read_b128 v[118:121], v99 offset:21824
	ds_read_b128 v[126:129], v99 offset:21888
	ds_read_b128 v[130:133], v99 offset:21952
	ds_read_b128 v[134:137], v96 offset:34816
	ds_read_b128 v[138:141], v96 offset:34880
	ds_read_b128 v[142:145], v96 offset:37120
	ds_read_b128 v[146:149], v96 offset:37184
	v_add_u32_e32 v101, v75, v83
	ds_read_b128 v[150:153], v101 offset:53248
	ds_read_b128 v[154:157], v101 offset:53312
	ds_read_b128 v[158:161], v101 offset:55552
	ds_read_b128 v[164:167], v101 offset:55616
	s_waitcnt lgkmcnt(14)
	v_mfma_f32_16x16x32_bf16 v[66:69], v[66:69], v[50:53], 0
	v_mfma_f32_16x16x32_bf16 v[66:69], v[102:105], v[54:57], v[66:69]
	s_waitcnt lgkmcnt(11)
	v_mfma_f32_16x16x32_bf16 v[102:105], v[114:117], v[50:53], 0
	s_waitcnt lgkmcnt(10)
	v_mfma_f32_16x16x32_bf16 v[102:105], v[118:121], v[54:57], v[102:105]
	s_waitcnt lgkmcnt(3)
	v_mfma_f32_16x16x32_bf16 v[22:25], v[134:137], v[150:153], v[22:25]
	s_waitcnt lgkmcnt(1)
	v_mfma_f32_16x16x32_bf16 v[26:29], v[134:137], v[158:161], v[26:29]
	v_mfma_f32_16x16x32_bf16 v[30:33], v[142:145], v[150:153], v[30:33]
	v_mfma_f32_16x16x32_bf16 v[34:37], v[142:145], v[158:161], v[34:37]
	v_mfma_f32_16x16x32_bf16 v[66:69], v[106:109], v[58:61], v[66:69]
	v_mfma_f32_16x16x32_bf16 v[102:105], v[126:129], v[58:61], v[102:105]
	v_mfma_f32_16x16x32_bf16 v[22:25], v[138:141], v[154:157], v[22:25]
	s_waitcnt lgkmcnt(0)
	v_mfma_f32_16x16x32_bf16 v[26:29], v[138:141], v[164:167], v[26:29]
	v_mfma_f32_16x16x32_bf16 v[30:33], v[146:149], v[154:157], v[30:33]
	v_mfma_f32_16x16x32_bf16 v[34:37], v[146:149], v[164:167], v[34:37]
	v_mfma_f32_16x16x32_bf16 v[66:69], v[110:113], v[62:65], v[66:69]
	v_mfma_f32_16x16x32_bf16 v[102:105], v[130:133], v[62:65], v[102:105]
	ds_read_b128 v[106:109], v99 offset:26112
	ds_read_b128 v[110:113], v99 offset:26176
	ds_read_b128 v[114:117], v99 offset:26240
	ds_read_b128 v[118:121], v99 offset:26304
	ds_read_b128 v[126:129], v97 offset:26112
	ds_read_b128 v[130:133], v97 offset:26176
	ds_read_b128 v[134:137], v97 offset:26240
	ds_read_b128 v[138:141], v97 offset:26304
	v_add_u32_e32 v101, 0xd000, v98
	ds_read2_b64 v[142:145], v101 offset1:4
	ds_read2_b64 v[146:149], v101 offset0:8 offset1:12
	ds_read_b128 v[150:153], v99 offset:57856
	ds_read_b128 v[154:157], v99 offset:57920
	ds_read_b128 v[158:161], v99 offset:57984
	ds_read_b128 v[164:167], v99 offset:58048
	v_add_u32_e32 v101, 0xd800, v98
	ds_read2_b64 v[168:171], v101 offset0:32 offset1:36
	ds_read2_b64 v[172:175], v101 offset0:40 offset1:44
	ds_read_b128 v[176:179], v99 offset:62208
	ds_read_b128 v[180:183], v99 offset:62272
	ds_read_b128 v[184:187], v99 offset:62336
	ds_read_b128 v[200:203], v99 offset:62400
	s_waitcnt lgkmcnt(14)
	v_mfma_f32_16x16x32_bf16 v[106:109], v[106:109], v[50:53], 0
	v_cndmask_b32_e64 v101, v66, 0, s[50:51]
	v_cndmask_b32_e64 v122, 0, v67, s[48:49]
	v_cndmask_b32_e64 v123, v68, 0, s[54:55]
	v_cndmask_b32_e64 v124, v69, 0, s[52:53]
	v_mfma_f32_16x16x32_bf16 v[66:69], v[110:113], v[54:57], v[106:109]
	v_cndmask_b32_e64 v223, v102, 0, s[58:59]
	v_mfma_f32_16x16x32_bf16 v[66:69], v[114:117], v[58:61], v[66:69]
	v_cndmask_b32_e64 v106, v103, 0, s[56:57]
	v_cndmask_b32_e64 v107, v104, 0, s[62:63]
	v_cndmask_b32_e64 v108, v105, 0, s[60:61]
	v_mfma_f32_16x16x32_bf16 v[66:69], v[118:121], v[62:65], v[66:69]
	v_mov_b32_e32 v111, v106
	v_mov_b32_e32 v110, v107
	v_mfma_f32_16x16x32_bf16 v[102:105], v[126:129], v[50:53], 0
	v_mov_b32_e32 v116, v108
	s_nop 2
	v_cndmask_b32_e64 v117, v66, 0, s[66:67]
	v_cndmask_b32_e64 v118, v67, 0, s[64:65]
	s_waitcnt lgkmcnt(9)
	v_mfma_f32_16x16x32_bf16 v[106:109], v[150:153], v[50:53], 0
	v_cndmask_b32_e64 v119, v68, 0, s[70:71]
	v_cndmask_b32_e64 v120, v69, 0, s[68:69]
	s_waitcnt lgkmcnt(3)
	v_mfma_f32_16x16x32_bf16 v[50:53], v[176:179], v[50:53], 0
	v_mov_b32_e32 v115, v122
	v_mov_b32_e32 v114, v123
	v_mfma_f32_16x16x32_bf16 v[102:105], v[130:133], v[54:57], v[102:105]
	v_mov_b32_e32 v113, v124
	v_mfma_f32_16x16x32_bf16 v[66:69], v[154:157], v[54:57], v[106:109]
	s_waitcnt lgkmcnt(2)
	v_mfma_f32_16x16x32_bf16 v[50:53], v[180:183], v[54:57], v[50:53]
	v_cvt_pk_bf16_f32 v57, v110, v116
	v_cvt_pk_bf16_f32 v56, v223, v111
	v_cvt_pk_bf16_f32 v55, v114, v113
	v_mfma_f32_16x16x32_bf16 v[102:105], v[134:137], v[58:61], v[102:105]
	v_cvt_pk_bf16_f32 v54, v101, v115
	v_mfma_f32_16x16x32_bf16 v[66:69], v[158:161], v[58:61], v[66:69]
	s_waitcnt lgkmcnt(1)
	v_mfma_f32_16x16x32_bf16 v[50:53], v[184:187], v[58:61], v[50:53]
	v_mfma_f32_16x16x32_bf16 v[102:105], v[138:141], v[62:65], v[102:105]
	v_mfma_f32_16x16x32_bf16 v[66:69], v[164:167], v[62:65], v[66:69]
	s_waitcnt lgkmcnt(0)
	v_mfma_f32_16x16x32_bf16 v[50:53], v[200:203], v[62:65], v[50:53]
	s_nop 4
	v_cndmask_b32_e64 v102, v102, 0, s[74:75]
	v_cndmask_b32_e64 v103, v103, 0, s[72:73]
	v_cndmask_b32_e64 v104, v104, 0, s[78:79]
	v_cndmask_b32_e64 v105, v105, 0, s[76:77]
	v_mfma_f32_16x16x32_bf16 v[58:61], v[142:145], v[54:57], v[66:69]
	v_mfma_f32_16x16x32_bf16 v[50:53], v[168:171], v[54:57], v[50:53]
	v_add_u32_e32 v54, s31, v74
	v_cvt_pk_bf16_f32 v65, v104, v105
	v_cvt_pk_bf16_f32 v64, v102, v103
	v_cvt_pk_bf16_f32 v63, v119, v120
	v_cvt_pk_bf16_f32 v62, v117, v118
	v_cmp_lt_i32_e64 s[4:5], s33, v54
	s_nop 0
	v_mfma_f32_16x16x32_bf16 v[58:61], v[146:149], v[62:65], v[58:61]
	v_cndmask_b32_e64 v55, v205, v206, s[4:5]
	v_add_u32_e32 v55, v55, v0
	v_cndmask_b32_e32 v54, v55, v54, vcc
	v_mfma_f32_16x16x32_bf16 v[50:53], v[172:175], v[62:65], v[50:53]
	v_ashrrev_i32_e32 v55, 31, v54
	v_lshl_add_u64 v[54:55], s[2:3], 0, v[54:55]
	s_nop 1
	v_lshlrev_b64 v[54:55], 11, v[54:55]
	v_lshl_add_u64 v[54:55], v[40:41], 0, v[54:55]
	v_cvt_pk_bf16_f32 v57, v60, v61
	v_cvt_pk_bf16_f32 v56, v58, v59
	global_store_dwordx2 v[54:55], v[56:57], off
	v_mov_b32_e32 v58, v51
	v_mov_b32_e32 v51, v52
	v_cvt_pk_bf16_f32 v51, v51, v53
	v_cvt_pk_bf16_f32 v50, v50, v58
	global_store_dwordx2 v[54:55], v[50:51], off offset:32
